# final base + scan prefetch blocks using 4 base addresses with immediate offsets (fewer address VALU)
# speedup vs baseline: 1.0137x; 1.0098x over previous
.Lsa_done_pre:
	s_branch .LBB0_311
.LBB0_310:
	s_or_b64 exec, exec, s[2:3]
	v_cndmask_b32_e64 v18, 0, v18, s[6:7]
	v_add_f32_e32 v19, v19, v18
	v_cndmask_b32_e64 v18, v18, v19, s[8:9]
	v_add_f32_e32 v16, v16, v18
	v_cndmask_b32_e64 v16, v18, v16, s[10:11]
	v_add_f32_e32 v17, v17, v16
	v_cndmask_b32_e64 v153, v16, v17, s[12:13]
	v_add_f32_e32 v16, v153, v120
	v_add_f32_e32 v17, v152, v153
	v_sub_f32_e32 v16, v127, v16
	v_sub_f32_e32 v17, v127, v17
	v_mul_f32_e32 v16, 0x3fb8aa3b, v16
	v_mul_f32_e32 v17, 0x3fb8aa3b, v17
	v_exp_f32_e32 v16, v16
	v_exp_f32_e32 v17, v17
	v_lshlrev_b32_e32 v121, 16, v121
	v_lshlrev_b32_e32 v122, 16, v122
	v_mul_f32_e32 v16, v16, v121
	v_mul_f32_e32 v17, v17, v122
	v_cvt_pk_bf16_f32 v16, v16, v17
	v_add_f32_e32 v17, v150, v153
	v_add_f32_e32 v18, v151, v153
	v_sub_f32_e32 v17, v127, v17
	v_sub_f32_e32 v18, v127, v18
	v_mul_f32_e32 v17, 0x3fb8aa3b, v17
	v_mul_f32_e32 v18, 0x3fb8aa3b, v18
	v_exp_f32_e32 v17, v17
	v_exp_f32_e32 v18, v18
	v_lshlrev_b32_e32 v123, 16, v123
	v_lshlrev_b32_e32 v126, 16, v126
	v_mul_f32_e32 v17, v17, v123
	v_mul_f32_e32 v18, v18, v126
	v_cvt_pk_bf16_f32 v17, v17, v18
	v_add_f32_e32 v18, v147, v153
	v_add_f32_e32 v19, v148, v153
	v_sub_f32_e32 v18, v127, v18
	v_sub_f32_e32 v19, v127, v19
	v_mul_f32_e32 v18, 0x3fb8aa3b, v18
	v_mul_f32_e32 v19, 0x3fb8aa3b, v19
	v_exp_f32_e32 v18, v18
	v_exp_f32_e32 v19, v19
	v_lshlrev_b32_e32 v128, 16, v128
	v_lshlrev_b32_e32 v131, 16, v131
	v_mul_f32_e32 v18, v18, v128
	v_mul_f32_e32 v19, v19, v131
	v_cvt_pk_bf16_f32 v18, v18, v19
	v_add_f32_e32 v19, v143, v153
	v_add_f32_e32 v120, v144, v153
	v_sub_f32_e32 v19, v127, v19
	v_sub_f32_e32 v120, v127, v120
	v_mul_f32_e32 v19, 0x3fb8aa3b, v19
	v_mul_f32_e32 v120, 0x3fb8aa3b, v120
	v_exp_f32_e32 v19, v19
	v_exp_f32_e32 v120, v120
	v_lshlrev_b32_e32 v132, 16, v132
	v_lshlrev_b32_e32 v133, 16, v133
	v_mul_f32_e32 v19, v19, v132
	v_mul_f32_e32 v120, v120, v133
	v_cvt_pk_bf16_f32 v19, v19, v120
	v_add_f32_e32 v120, v138, v153
	v_add_f32_e32 v121, v139, v153
	v_sub_f32_e32 v120, v127, v120
	v_sub_f32_e32 v121, v127, v121
	v_mul_f32_e32 v120, 0x3fb8aa3b, v120
	v_mul_f32_e32 v121, 0x3fb8aa3b, v121
	v_exp_f32_e32 v120, v120
	v_exp_f32_e32 v121, v121
	v_lshlrev_b32_e32 v136, 16, v136
	v_lshlrev_b32_e32 v137, 16, v137
	v_mul_f32_e32 v120, v120, v136
	v_mul_f32_e32 v121, v121, v137
	v_cvt_pk_bf16_f32 v120, v120, v121
	v_add_f32_e32 v121, v134, v153
	v_add_f32_e32 v122, v135, v153
	v_sub_f32_e32 v121, v127, v121
	v_sub_f32_e32 v122, v127, v122
	v_mul_f32_e32 v121, 0x3fb8aa3b, v121
	v_mul_f32_e32 v122, 0x3fb8aa3b, v122
	v_exp_f32_e32 v121, v121
	v_exp_f32_e32 v122, v122
	v_lshlrev_b32_e32 v140, 16, v140
	v_lshlrev_b32_e32 v141, 16, v141
	v_mul_f32_e32 v121, v121, v140
	v_mul_f32_e32 v122, v122, v141
	v_cvt_pk_bf16_f32 v121, v121, v122
	v_add_f32_e32 v122, v129, v153
	v_add_f32_e32 v123, v130, v153
	v_sub_f32_e32 v122, v127, v122
	v_sub_f32_e32 v123, v127, v123
	v_mul_f32_e32 v122, 0x3fb8aa3b, v122
	v_mul_f32_e32 v123, 0x3fb8aa3b, v123
	v_exp_f32_e32 v122, v122
	v_exp_f32_e32 v123, v123
	v_lshlrev_b32_e32 v142, 16, v142
	v_lshlrev_b32_e32 v145, 16, v145
	v_mul_f32_e32 v122, v122, v142
	v_mul_f32_e32 v123, v123, v145
	v_cvt_pk_bf16_f32 v122, v122, v123
	v_add_f32_e32 v123, v124, v153
	v_add_f32_e32 v124, v125, v153
	v_sub_f32_e32 v123, v127, v123
	v_mul_f32_e32 v123, 0x3fb8aa3b, v123
	v_sub_f32_e32 v124, v127, v124
	v_exp_f32_e32 v123, v123
	v_mul_f32_e32 v124, 0x3fb8aa3b, v124
	v_exp_f32_e32 v124, v124
	v_lshlrev_b32_e32 v146, 16, v146
	v_lshlrev_b32_e32 v149, 16, v149
	v_mul_f32_e32 v123, v123, v146
	v_mul_f32_e32 v124, v124, v149
	v_cvt_pk_bf16_f32 v123, v123, v124
	ds_write_b128 v93, v[16:19] offset:34816
	ds_write_b128 v93, v[120:123] offset:34832
	s_waitcnt lgkmcnt(0)
	s_barrier
	ds_read_b128 v[16:19], v95
	ds_read_b128 v[120:123], v24 offset:34816
	ds_read_b128 v[128:131], v94 offset:53248
	ds_read_b128 v[132:135], v94 offset:55552
	ds_read_b128 v[136:139], v94 offset:57856
	ds_read_b128 v[140:143], v94 offset:60160
	ds_read_b128 v[124:127], v24 offset:34880
	ds_read_b128 v[144:147], v94 offset:53312
	ds_read_b128 v[148:151], v94 offset:55616
	ds_read_b128 v[152:155], v94 offset:57920
	ds_read_b128 v[236:239], v94 offset:60224
	s_sub_i32 s25, s25, 64
	s_add_i32 s23, s23, 64
	s_cmpk_eq_i32 s25, 0xffc0
	s_waitcnt lgkmcnt(10)
	v_pk_mul_f32 v[0:1], v[0:1], v[16:17]
	v_pk_mul_f32 v[2:3], v[2:3], v[18:19]
	v_pk_mul_f32 v[4:5], v[4:5], v[16:17]
	v_pk_mul_f32 v[6:7], v[6:7], v[18:19]
	v_pk_mul_f32 v[8:9], v[8:9], v[16:17]
	v_pk_mul_f32 v[10:11], v[10:11], v[18:19]
	v_pk_mul_f32 v[12:13], v[12:13], v[16:17]
	v_pk_mul_f32 v[14:15], v[14:15], v[18:19]
	s_waitcnt lgkmcnt(8)
	v_mfma_f32_16x16x32_bf16 v[0:3], v[120:123], v[128:131], v[0:3]
	s_waitcnt lgkmcnt(7)
	v_mfma_f32_16x16x32_bf16 v[4:7], v[120:123], v[132:135], v[4:7]
	s_waitcnt lgkmcnt(6)
	v_mfma_f32_16x16x32_bf16 v[8:11], v[120:123], v[136:139], v[8:11]
	s_waitcnt lgkmcnt(5)
	v_mfma_f32_16x16x32_bf16 v[12:15], v[120:123], v[140:143], v[12:15]
	s_waitcnt lgkmcnt(3)
	v_mfma_f32_16x16x32_bf16 v[0:3], v[124:127], v[144:147], v[0:3]
	s_waitcnt lgkmcnt(2)
	v_mfma_f32_16x16x32_bf16 v[4:7], v[124:127], v[148:151], v[4:7]
	s_waitcnt lgkmcnt(1)
	v_mfma_f32_16x16x32_bf16 v[8:11], v[124:127], v[152:155], v[8:11]
	s_waitcnt lgkmcnt(0)
	s_barrier
	v_mfma_f32_16x16x32_bf16 v[12:15], v[124:127], v[236:239], v[12:15]
	s_cbranch_scc1 .LBB0_313
